# all small edits together: prefetch in norms, M1/G3 epilogues, phase-A conversion, packed row sums in N2, phase-C DMA placement, barrier generation-word atomics dropped
# speedup vs baseline: 1.0080x; 1.0054x over previous
; __device__ __forceinline__ float exp2f_(float x) { return __builtin_amdgcn_exp2f(x); }
; __device__ __forceinline__ f32x4 mfma16(bf16x8 a, bf16x8 b, f32x4 c) { return __builtin_amdgcn_mfma_f32_16x16x32_bf16(a, b, c, 0, 0, 0); }
; __device__ __forceinline__ void nsa_block_step(const bf16_t* Ks, const bf16_t* VT, const bf16x8 (&qf)[2][2], f32x4 (&O)[2][4], float (&m)[2], float (&l)[2],
;                                                int klo, int khi, int r, int q) {
;     ...
;         float ls = 0.f;
; #pragma unroll
;         for (int kt = 0; kt < 4; kt++)
; #pragma unroll
;             for (int j = 0; j < 4; j++) { const float pv = exp2f_(s[x][kt][j] - mnew); s[x][kt][j] = pv; ls += pv; }
;         l[x] = l[x] * alpha + ls;
; #pragma unroll
;         for (int dt = 0; dt < 4; dt++) O[x][dt] *= alpha;
; #pragma unroll
;         for (int s2 = 0; s2 < 2; s2++) {
;             const u32x4 t4 = {pack2(s[x][2 * s2][0], s[x][2 * s2][1]), pack2(s[x][2 * s2][2], s[x][2 * s2][3]),
;                               pack2(s[x][2 * s2 + 1][0], s[x][2 * s2 + 1][1]), pack2(s[x][2 * s2 + 1][2], s[x][2 * s2 + 1][3])};
;             pbv[x][s2] = __builtin_bit_cast(bf16x8, t4);
;         }
;     }
; #pragma unroll
;     for (int s2 = 0; s2 < 2; s2++)
; #pragma unroll
;         for (int dt = 0; dt < 4; dt++) {
;             const u32x2 lo = *(const u32x2*)(VT + (dt * 16 + r) * 72 + (2 * s2) * 16 + 4 * q);
;             const u32x2 hi = *(const u32x2*)(VT + (dt * 16 + r) * 72 + (2 * s2 + 1) * 16 + 4 * q);
;             const bf16x8 va = mk_frag(lo, hi);
; #pragma unroll
;             for (int x = 0; x < 2; x++) O[x][dt] = mfma16(va, pbv[x][s2], O[x][dt]);
.Ln2_fast:
	ds_read2_b64 v[200:203], v216 offset1:4
	ds_read2_b64 v[204:207], v217 offset0:32 offset1:36
	ds_read2_b64 v[208:211], v218 offset0:64 offset1:68
	ds_read2_b64 v[212:215], v219 offset0:96 offset1:100
	v_exp_f32_e32 v80, v80
	v_exp_f32_e32 v81, v81
	v_exp_f32_e32 v82, v82
	v_exp_f32_e32 v83, v83
	v_exp_f32_e32 v72, v72
	v_exp_f32_e32 v73, v73
	v_exp_f32_e32 v74, v74
	v_exp_f32_e32 v75, v75
	ds_read2_b64 v[224:227], v216 offset0:8 offset1:12
	ds_read2_b64 v[228:231], v217 offset0:40 offset1:44
	v_exp_f32_e32 v68, v68
	v_exp_f32_e32 v69, v69
	v_exp_f32_e32 v70, v70
	v_exp_f32_e32 v71, v71
	v_exp_f32_e32 v64, v64
	v_exp_f32_e32 v65, v65
	v_exp_f32_e32 v66, v66
	v_exp_f32_e32 v67, v67
	ds_read2_b64 v[232:235], v218 offset0:72 offset1:76
	ds_read2_b64 v[236:239], v219 offset0:104 offset1:108
	v_cvt_pk_bf16_f32 v184, v80, v81
	v_cvt_pk_bf16_f32 v185, v82, v83
	v_cvt_pk_bf16_f32 v186, v72, v73
	v_cvt_pk_bf16_f32 v187, v74, v75
	v_cvt_pk_bf16_f32 v192, v68, v69
	v_cvt_pk_bf16_f32 v193, v70, v71
	v_cvt_pk_bf16_f32 v194, v64, v65
	v_cvt_pk_bf16_f32 v195, v66, v67
	v_exp_f32_e32 v84, v84
	v_exp_f32_e32 v85, v85
	s_waitcnt lgkmcnt(7)
	v_mfma_f32_16x16x32_bf16 v[52:55], v[200:203], v[184:187], v[52:55]
	v_exp_f32_e32 v86, v86
	v_exp_f32_e32 v87, v87
	v_mfma_f32_16x16x32_bf16 v[36:39], v[200:203], v[192:195], v[36:39]
	v_exp_f32_e32 v76, v76
	v_exp_f32_e32 v77, v77
	s_waitcnt lgkmcnt(6)
	v_mfma_f32_16x16x32_bf16 v[48:51], v[204:207], v[184:187], v[48:51]
	v_exp_f32_e32 v78, v78
	v_exp_f32_e32 v79, v79
	v_mfma_f32_16x16x32_bf16 v[32:35], v[204:207], v[192:195], v[32:35]
	v_exp_f32_e32 v60, v60
	v_exp_f32_e32 v61, v61
	s_waitcnt lgkmcnt(5)
	v_mfma_f32_16x16x32_bf16 v[44:47], v[208:211], v[184:187], v[44:47]
	v_exp_f32_e32 v62, v62
	v_exp_f32_e32 v63, v63
	v_mfma_f32_16x16x32_bf16 v[28:31], v[208:211], v[192:195], v[28:31]
	v_exp_f32_e32 v56, v56
	v_exp_f32_e32 v57, v57
	s_waitcnt lgkmcnt(4)
	v_mfma_f32_16x16x32_bf16 v[40:43], v[212:215], v[184:187], v[40:43]
	v_exp_f32_e32 v58, v58
	v_exp_f32_e32 v59, v59
	v_mfma_f32_16x16x32_bf16 v[24:27], v[212:215], v[192:195], v[24:27]
	v_cvt_pk_bf16_f32 v188, v84, v85
	v_cvt_pk_bf16_f32 v189, v86, v87
	v_cvt_pk_bf16_f32 v190, v76, v77
	v_cvt_pk_bf16_f32 v191, v78, v79
	v_cvt_pk_bf16_f32 v196, v60, v61
	v_cvt_pk_bf16_f32 v197, v62, v63
	v_cvt_pk_bf16_f32 v198, v56, v57
	v_cvt_pk_bf16_f32 v199, v58, v59
	s_waitcnt lgkmcnt(3)
	v_mfma_f32_16x16x32_bf16 v[52:55], v[224:227], v[188:191], v[52:55]
	v_mfma_f32_16x16x32_bf16 v[36:39], v[224:227], v[196:199], v[36:39]
	s_waitcnt lgkmcnt(2)
	v_mfma_f32_16x16x32_bf16 v[48:51], v[228:231], v[188:191], v[48:51]
	v_mfma_f32_16x16x32_bf16 v[32:35], v[228:231], v[196:199], v[32:35]
	s_waitcnt lgkmcnt(1)
	v_mfma_f32_16x16x32_bf16 v[44:47], v[232:235], v[188:191], v[44:47]
	v_mfma_f32_16x16x32_bf16 v[28:31], v[232:235], v[196:199], v[28:31]
	s_waitcnt lgkmcnt(0)
	v_mfma_f32_16x16x32_bf16 v[40:43], v[236:239], v[188:191], v[40:43]
	v_mfma_f32_16x16x32_bf16 v[24:27], v[236:239], v[196:199], v[24:27]
	v_pk_add_f32 v[184:185], v[80:81], v[82:83]
	v_pk_add_f32 v[192:193], v[68:69], v[70:71]
	v_pk_add_f32 v[186:187], v[72:73], v[74:75]
	v_pk_add_f32 v[194:195], v[64:65], v[66:67]
	v_pk_add_f32 v[184:185], v[184:185], v[84:85]
	v_pk_add_f32 v[192:193], v[192:193], v[60:61]
	v_pk_add_f32 v[186:187], v[186:187], v[86:87]
	v_pk_add_f32 v[194:195], v[194:195], v[62:63]
	v_pk_add_f32 v[184:185], v[184:185], v[76:77]
	v_pk_add_f32 v[192:193], v[192:193], v[56:57]
	v_pk_add_f32 v[186:187], v[186:187], v[78:79]
	v_pk_add_f32 v[194:195], v[194:195], v[58:59]
	v_pk_add_f32 v[184:185], v[184:185], v[186:187]
	v_pk_add_f32 v[192:193], v[192:193], v[194:195]
	v_add_f32_e32 v221, v184, v185
	v_add_f32_e32 v220, v192, v193
	s_cmp_lg_u32 s52, s34
	s_cselect_b64 vcc, -1, 0
	v_mov_b32_e32 v88, v103
	v_mov_b32_e32 v97, v102
	v_pk_add_f32 v[100:101], v[100:101], v[220:221]
	s_branch .Ln2_tail
